# attn0 fast path v3: lazy rescale (threshold 8, exact rare path) in the hand-scheduled unmasked tile body; attn1 unchanged from P4c
# speedup vs baseline: 1.0089x; 1.0048x over previous
; #define LAS __attribute__((address_space(3)))
; __device__ __forceinline__ float shx(float v, int lane, int o) { return __builtin_bit_cast(float, __builtin_amdgcn_ds_bpermute((lane ^ o) << 2, __builtin_bit_cast(int, v))); }
; __device__ __forceinline__ int crow(int i, int hi) { return (i & 3) + 8 * (i >> 2) + 4 * hi; }
; #define MFMA32(a, b, c) __builtin_amdgcn_mfma_f32_32x32x16_bf16((a), (b), (c), 0, 0, 0)
; template <int DQ, bool BIAS>
; __device__ __forceinline__ void attn_item_l0(const AttnItem& A, LAS unsigned char* lds, int wave_s_) {
;     ...
;             LAS unsigned char* kb = lds + buf * OKBUF; LAS unsigned char* vb = lds + 2 * OKBUF + buf * OVBUF;
;             f32x16 s[2][2];
; #pragma unroll
;             for (int kbk = 0; kbk < 2; ++kbk) {
; #pragma unroll
;                 for (int qb = 0; qb < 2; ++qb)
; #pragma unroll
;                     for (int i = 0; i < 16; ++i) s[kbk][qb][i] = 0.f;
; #pragma unroll
;                 for (int kk = 0; kk < NKK; ++kk) {
;                     const bf16x8 kf = *(const LAS bf16x8*)(kb + ((32 * kbk + r32) * OKSTR + 16 * kk + 8 * hi) * 2);
;                     s[kbk][0] = MFMA32(kf, qf[0][kk], s[kbk][0]);
;                     s[kbk][1] = MFMA32(kf, qf[1][kk], s[kbk][1]);
;                 }
;             }
; #pragma unroll
;             for (int qb = 0; qb < 2; ++qb) {
;                 const int qk = A.q_kidx0 + 64 * w + 32 * qb + r32;
;                 float mx = -3.0e38f;
; #pragma unroll
;                 for (int kbk = 0; kbk < 2; ++kbk)
; #pragma unroll
;                     for (int i = 0; i < 16; ++i) {
;                         const int kidx = 64 * t + 32 * kbk + crow(i, hi);
;                         float v = s[kbk][qb][i] * A.scale2;
;                         if (BIAS) v += lut[kidx - qk + LUT0];
;                         if (kidx >= A.nkeys) v = -1.0e30f;
;                         s[kbk][qb][i] = v; mx = fmaxf(mx, v);
;                     }
;                 mx = fmaxf(mx, shx(mx, lane, 32));
.La0_fast:
	s_mul_i32 s4, s72, 0x3400
	v_add3_u32 v176, v247, s4, v249
	ds_read_b128 v[180:183], v176 offset:0
	ds_read_b128 v[184:187], v176 offset:32
	ds_read_b128 v[188:191], v176 offset:64
	ds_read_b128 v[192:195], v176 offset:96
	ds_read2_b32 v[206:207], v251 offset0:32 offset1:33
	ds_read2_b32 v[208:209], v251 offset0:34 offset1:35
	ds_read2_b32 v[210:211], v251 offset0:40 offset1:41
	ds_read2_b32 v[212:213], v251 offset0:42 offset1:43
	ds_read2_b32 v[214:215], v251 offset0:48 offset1:49
	ds_read2_b32 v[216:217], v251 offset0:50 offset1:51
	ds_read2_b32 v[218:219], v251 offset0:56 offset1:57
	ds_read2_b32 v[220:221], v251 offset0:58 offset1:59
	s_mul_i32 s4, s72, 0x2200
	v_add3_u32 v244, v248, s4, v250
	v_add_u32_e32 v253, 0x7800, v244
	v_add_u32_e32 v244, 0x6800, v244
	s_waitcnt lgkmcnt(11)
	v_mfma_f32_32x32x16_bf16 v[112:127], v[180:183], v[132:135], 0
	v_mfma_f32_32x32x16_bf16 v[80:95], v[180:183], v[152:155], 0
	ds_read_b128 v[180:183], v176 offset:6656
	s_waitcnt lgkmcnt(11)
	v_mfma_f32_32x32x16_bf16 v[112:127], v[184:187], v[136:139], v[112:127]
	v_mfma_f32_32x32x16_bf16 v[80:95], v[184:187], v[156:159], v[80:95]
	ds_read_b128 v[184:187], v176 offset:6688
	s_waitcnt lgkmcnt(11)
	v_mfma_f32_32x32x16_bf16 v[112:127], v[188:191], v[140:143], v[112:127]
	v_mfma_f32_32x32x16_bf16 v[80:95], v[188:191], v[160:163], v[80:95]
	ds_read_b128 v[188:191], v176 offset:6720
	s_waitcnt lgkmcnt(11)
	v_mfma_f32_32x32x16_bf16 v[112:127], v[192:195], v[144:147], v[112:127]
	v_mfma_f32_32x32x16_bf16 v[80:95], v[192:195], v[164:167], v[80:95]
	ds_read_b128 v[192:195], v176 offset:6752
	s_waitcnt lgkmcnt(3)
	v_mfma_f32_32x32x16_bf16 v[96:111], v[180:183], v[132:135], 0
	v_mfma_f32_32x32x16_bf16 v[64:79], v[180:183], v[152:155], 0
	ds_read2_b32 v[222:223], v251 offset0:0 offset1:1
	ds_read2_b32 v[224:225], v251 offset0:2 offset1:3
	ds_read2_b32 v[226:227], v251 offset0:8 offset1:9
	ds_read2_b32 v[228:229], v251 offset0:10 offset1:11
	ds_read2_b32 v[230:231], v251 offset0:16 offset1:17
	ds_read2_b32 v[232:233], v251 offset0:18 offset1:19
	ds_read2_b32 v[238:239], v251 offset0:24 offset1:25
	ds_read2_b32 v[240:241], v251 offset0:26 offset1:27
	v_fmamk_f32 v112, v112, 0x3e38aa3b, v206
	v_fmamk_f32 v113, v113, 0x3e38aa3b, v207
	v_fmamk_f32 v114, v114, 0x3e38aa3b, v208
	v_fmamk_f32 v115, v115, 0x3e38aa3b, v209
	v_fmamk_f32 v116, v116, 0x3e38aa3b, v210
	v_max3_f32 v234, v112, v113, v114
	s_waitcnt lgkmcnt(10)
	v_mfma_f32_32x32x16_bf16 v[96:111], v[184:187], v[136:139], v[96:111]
	v_mfma_f32_32x32x16_bf16 v[64:79], v[184:187], v[156:159], v[64:79]
	v_fmamk_f32 v117, v117, 0x3e38aa3b, v211
	v_fmamk_f32 v118, v118, 0x3e38aa3b, v212
	v_max3_f32 v234, v234, v115, v116
	v_fmamk_f32 v119, v119, 0x3e38aa3b, v213
	v_fmamk_f32 v120, v120, 0x3e38aa3b, v214
	v_max3_f32 v234, v234, v117, v118
	v_fmamk_f32 v121, v121, 0x3e38aa3b, v215
	v_fmamk_f32 v122, v122, 0x3e38aa3b, v216
	s_waitcnt lgkmcnt(9)
	v_mfma_f32_32x32x16_bf16 v[96:111], v[188:191], v[140:143], v[96:111]
	v_mfma_f32_32x32x16_bf16 v[64:79], v[188:191], v[160:163], v[64:79]
	v_max3_f32 v234, v234, v119, v120
	v_fmamk_f32 v123, v123, 0x3e38aa3b, v217
	v_fmamk_f32 v124, v124, 0x3e38aa3b, v218
	v_max3_f32 v234, v234, v121, v122
	v_fmamk_f32 v125, v125, 0x3e38aa3b, v219
	v_fmamk_f32 v126, v126, 0x3e38aa3b, v220
	v_max3_f32 v234, v234, v123, v124
	v_fmamk_f32 v127, v127, 0x3e38aa3b, v221
	s_waitcnt lgkmcnt(8)
	v_mfma_f32_32x32x16_bf16 v[96:111], v[192:195], v[144:147], v[96:111]
	v_mfma_f32_32x32x16_bf16 v[64:79], v[192:195], v[164:167], v[64:79]
	v_max3_f32 v234, v234, v125, v126
	v_max_f32_e32 v234, v234, v127
	s_waitcnt lgkmcnt(0)
	ds_read2_b32 v[180:181], v251 offset0:64 offset1:65
	ds_read2_b32 v[182:183], v251 offset0:66 offset1:67
	ds_read2_b32 v[184:185], v251 offset0:72 offset1:73
	ds_read2_b32 v[186:187], v251 offset0:74 offset1:75
	ds_read2_b32 v[188:189], v251 offset0:80 offset1:81
	ds_read2_b32 v[190:191], v251 offset0:82 offset1:83
	ds_read2_b32 v[192:193], v251 offset0:88 offset1:89
	ds_read2_b32 v[194:195], v251 offset0:90 offset1:91
	v_fmamk_f32 v80, v80, 0x3e38aa3b, v222
	v_fmamk_f32 v81, v81, 0x3e38aa3b, v223
	v_fmamk_f32 v82, v82, 0x3e38aa3b, v224
	v_fmamk_f32 v83, v83, 0x3e38aa3b, v225
	v_fmamk_f32 v84, v84, 0x3e38aa3b, v226
	v_max3_f32 v235, v80, v81, v82
	v_fmamk_f32 v85, v85, 0x3e38aa3b, v227
	v_fmamk_f32 v86, v86, 0x3e38aa3b, v228
	v_max3_f32 v235, v235, v83, v84
	v_fmamk_f32 v87, v87, 0x3e38aa3b, v229
	v_fmamk_f32 v88, v88, 0x3e38aa3b, v230
	v_max3_f32 v235, v235, v85, v86
	v_fmamk_f32 v89, v89, 0x3e38aa3b, v231
	v_fmamk_f32 v90, v90, 0x3e38aa3b, v232
	v_max3_f32 v235, v235, v87, v88
	v_fmamk_f32 v91, v91, 0x3e38aa3b, v233
	v_fmamk_f32 v92, v92, 0x3e38aa3b, v238
	v_max3_f32 v235, v235, v89, v90
	v_fmamk_f32 v93, v93, 0x3e38aa3b, v239
	v_fmamk_f32 v94, v94, 0x3e38aa3b, v240
	v_max3_f32 v235, v235, v91, v92
	v_fmamk_f32 v95, v95, 0x3e38aa3b, v241
	v_max3_f32 v235, v235, v93, v94
	v_max_f32_e32 v235, v235, v95
	v_fmamk_f32 v64, v64, 0x3e38aa3b, v206
	v_fmamk_f32 v65, v65, 0x3e38aa3b, v207
	v_fmamk_f32 v66, v66, 0x3e38aa3b, v208
	v_fmamk_f32 v67, v67, 0x3e38aa3b, v209
	v_max3_f32 v235, v235, v64, v65
	v_fmamk_f32 v68, v68, 0x3e38aa3b, v210
	v_fmamk_f32 v69, v69, 0x3e38aa3b, v211
	v_max3_f32 v235, v235, v66, v67
	v_fmamk_f32 v70, v70, 0x3e38aa3b, v212
	v_fmamk_f32 v71, v71, 0x3e38aa3b, v213
	v_max3_f32 v235, v235, v68, v69
	v_fmamk_f32 v72, v72, 0x3e38aa3b, v214
	v_fmamk_f32 v73, v73, 0x3e38aa3b, v215
	v_max3_f32 v235, v235, v70, v71
	v_fmamk_f32 v74, v74, 0x3e38aa3b, v216
	v_fmamk_f32 v75, v75, 0x3e38aa3b, v217
	v_max3_f32 v235, v235, v72, v73
	v_fmamk_f32 v76, v76, 0x3e38aa3b, v218
	v_fmamk_f32 v77, v77, 0x3e38aa3b, v219
	v_max3_f32 v235, v235, v74, v75
	v_fmamk_f32 v78, v78, 0x3e38aa3b, v220
	v_fmamk_f32 v79, v79, 0x3e38aa3b, v221
	v_max3_f32 v235, v235, v76, v77
	v_max3_f32 v235, v235, v78, v79
	s_waitcnt lgkmcnt(0)
; __device__ __forceinline__ float shx(float v, int lane, int o) { return __builtin_bit_cast(float, __builtin_amdgcn_ds_bpermute((lane ^ o) << 2, __builtin_bit_cast(int, v))); }
; __device__ __forceinline__ float swapmax(float v, int hi) { return fmaxf(v, xhalf(v, hi)); }
; template <int DQ, bool BIAS, bool TAIL>
; __device__ __forceinline__ void attn_item(const AttnItem& A, LAS unsigned char* lds, int wave_s_) {
;     ...
;                     mx[qb] = swapmax(m, hi) - mref[qb];
;                 }
;                 const bool need0 = first || mx[0] > RESCALE_THR, need1 = first || mx[1] > RESCALE_THR;
;                 if (__builtin_amdgcn_ballot_w64(need0 || need1) != 0ull) {
; #pragma unroll
;                     for (int qb = 0; qb < 2; ++qb) {
;                         const float delta = (qb == 0 ? need0 : need1) ? mx[qb] : 0.f, alpha = __builtin_amdgcn_exp2f(-delta);
; #pragma unroll
;                         for (int i = 0; i < 16; ++i) { o[0][qb][i] *= alpha; o[1][qb][i] *= alpha; }
;                         lrun[qb] *= alpha; mref[qb] += delta;
;                     }
;                     first = false;
;                 }
; #pragma unroll
;                 for (int qb = 0; qb < 2; ++qb) { float l4[4] = {0.f, 0.f, 0.f, 0.f};
; #pragma unroll
;                     for (int i = 0; i < 16; ++i) { const float pv = __builtin_amdgcn_exp2f(s[qb][i] - mref[qb]); s[qb][i] = pv; l4[i & 3] += pv; }
;                     lrun[qb] += (l4[0] + l4[1]) + (l4[2] + l4[3]); }
; template <int DQ, bool BIAS>
; __device__ __forceinline__ void attn_item_l0(const AttnItem& A, LAS unsigned char* lds, int wave_s_) {
;     ...
;                 mx = fmaxf(mx, shx(mx, lane, 32));
;                 const float mnew = fmaxf(mrun[qb], mx), alpha = __builtin_amdgcn_exp2f(mrun[qb] - mnew);
;                 mrun[qb] = mnew;
;                 float ls = 0.f;
; #pragma unroll
;                 for (int kbk = 0; kbk < 2; ++kbk)
; #pragma unroll
;                     for (int i = 0; i < 16; ++i) { const float p = __builtin_amdgcn_exp2f(s[kbk][qb][i] - mnew); s[kbk][qb][i] = p; ls += p; }
;                 lrun[qb] = lrun[qb] * alpha + ls;
	v_fmamk_f32 v96, v96, 0x3e38aa3b, v180
	v_fmamk_f32 v97, v97, 0x3e38aa3b, v181
	v_fmamk_f32 v98, v98, 0x3e38aa3b, v182
	v_fmamk_f32 v99, v99, 0x3e38aa3b, v183
	v_max3_f32 v234, v234, v96, v97
	v_fmamk_f32 v100, v100, 0x3e38aa3b, v184
	v_fmamk_f32 v101, v101, 0x3e38aa3b, v185
	v_max3_f32 v234, v234, v98, v99
	v_fmamk_f32 v102, v102, 0x3e38aa3b, v186
	v_fmamk_f32 v103, v103, 0x3e38aa3b, v187
	v_max3_f32 v234, v234, v100, v101
	v_fmamk_f32 v104, v104, 0x3e38aa3b, v188
	v_fmamk_f32 v105, v105, 0x3e38aa3b, v189
	v_max3_f32 v234, v234, v102, v103
	v_fmamk_f32 v106, v106, 0x3e38aa3b, v190
	v_fmamk_f32 v107, v107, 0x3e38aa3b, v191
	v_max3_f32 v234, v234, v104, v105
	v_fmamk_f32 v108, v108, 0x3e38aa3b, v192
	v_fmamk_f32 v109, v109, 0x3e38aa3b, v193
	v_max3_f32 v234, v234, v106, v107
	v_fmamk_f32 v110, v110, 0x3e38aa3b, v194
	v_fmamk_f32 v111, v111, 0x3e38aa3b, v195
	v_max3_f32 v234, v234, v108, v109
	v_max3_f32 v234, v234, v110, v111
	ds_read2_b64 v[206:209], v244 offset0:0 offset1:2
	ds_read2_b64 v[210:213], v253 offset0:32 offset1:34
	ds_read2_b64 v[214:217], v244 offset0:4 offset1:6
	ds_read2_b64 v[218:221], v253 offset0:36 offset1:38
	ds_read2_b64 v[222:225], v244 offset0:8 offset1:10
	ds_read2_b64 v[226:229], v253 offset0:40 offset1:42
	ds_read2_b64 v[230:233], v244 offset0:12 offset1:14
	ds_read2_b64 v[180:183], v253 offset0:44 offset1:46
	s_mov_b32 s12, 0x41000000
	v_sub_f32_e32 v199, v235, v179
	v_sub_f32_e32 v198, v234, v178
	v_cmp_lt_f32_e32 vcc, s12, v199
	s_or_b32 s10, vcc_lo, vcc_hi
	v_cmp_lt_f32_e32 vcc, s12, v198
	s_mov_b32 s11, s10
	s_or_b32 s8, vcc_lo, vcc_hi
	s_mov_b32 s9, s8
	s_or_b64 s[14:15], s[8:9], s[10:11]
	s_cbranch_scc1 .La0_rare
.La0_back:
	v_sub_f32_e32 v80, v80, v179
	v_sub_f32_e32 v81, v81, v179
	v_sub_f32_e32 v82, v82, v179
	v_exp_f32_e32 v80, v80
	v_sub_f32_e32 v83, v83, v179
	v_exp_f32_e32 v81, v81
	v_sub_f32_e32 v84, v84, v179
	v_exp_f32_e32 v82, v82
	v_sub_f32_e32 v85, v85, v179
	v_exp_f32_e32 v83, v83
	v_sub_f32_e32 v86, v86, v179
	v_exp_f32_e32 v84, v84
	v_add_f32_e32 v235, v80, v81
	v_sub_f32_e32 v87, v87, v179
	v_exp_f32_e32 v85, v85
	v_add_f32_e32 v235, v235, v82
	v_sub_f32_e32 v88, v88, v179
	v_exp_f32_e32 v86, v86
	v_add_f32_e32 v235, v235, v83
	v_sub_f32_e32 v89, v89, v179
	v_exp_f32_e32 v87, v87
	v_add_f32_e32 v235, v235, v84
	v_sub_f32_e32 v90, v90, v179
	v_exp_f32_e32 v88, v88
	v_add_f32_e32 v235, v235, v85
	v_sub_f32_e32 v91, v91, v179
	v_exp_f32_e32 v89, v89
	v_add_f32_e32 v235, v235, v86
	v_sub_f32_e32 v92, v92, v179
	v_exp_f32_e32 v90, v90
	v_add_f32_e32 v235, v235, v87
	v_sub_f32_e32 v93, v93, v179
	v_exp_f32_e32 v91, v91
	v_add_f32_e32 v235, v235, v88
	v_sub_f32_e32 v94, v94, v179
	v_exp_f32_e32 v92, v92
	v_add_f32_e32 v235, v235, v89
	v_sub_f32_e32 v95, v95, v179
	v_exp_f32_e32 v93, v93
	v_add_f32_e32 v235, v235, v90
	v_sub_f32_e32 v64, v64, v179
	v_exp_f32_e32 v94, v94
	v_add_f32_e32 v235, v235, v91
	v_sub_f32_e32 v65, v65, v179
	v_exp_f32_e32 v95, v95
	v_add_f32_e32 v235, v235, v92
	v_sub_f32_e32 v66, v66, v179
	v_exp_f32_e32 v64, v64
	v_add_f32_e32 v235, v235, v93
	v_sub_f32_e32 v67, v67, v179
	v_exp_f32_e32 v65, v65
	v_add_f32_e32 v235, v235, v94
	v_sub_f32_e32 v68, v68, v179
	v_exp_f32_e32 v66, v66
	v_add_f32_e32 v235, v235, v95
	v_sub_f32_e32 v69, v69, v179
	v_exp_f32_e32 v67, v67
	v_add_f32_e32 v235, v235, v64
	v_sub_f32_e32 v70, v70, v179
	v_exp_f32_e32 v68, v68
	v_add_f32_e32 v235, v235, v65
	v_sub_f32_e32 v71, v71, v179
	v_exp_f32_e32 v69, v69
	v_add_f32_e32 v235, v235, v66
	v_sub_f32_e32 v72, v72, v179
	v_exp_f32_e32 v70, v70
	v_add_f32_e32 v235, v235, v67
	v_sub_f32_e32 v73, v73, v179
	v_exp_f32_e32 v71, v71
	v_add_f32_e32 v235, v235, v68
	v_sub_f32_e32 v74, v74, v179
	v_exp_f32_e32 v72, v72
	v_add_f32_e32 v235, v235, v69
	v_sub_f32_e32 v75, v75, v179
	v_exp_f32_e32 v73, v73
	v_add_f32_e32 v235, v235, v70
	v_sub_f32_e32 v76, v76, v179
	v_exp_f32_e32 v74, v74
	v_add_f32_e32 v235, v235, v71
	v_sub_f32_e32 v77, v77, v179
	v_exp_f32_e32 v75, v75
	v_add_f32_e32 v235, v235, v72
	v_sub_f32_e32 v78, v78, v179
	v_exp_f32_e32 v76, v76
	v_add_f32_e32 v235, v235, v73
	v_sub_f32_e32 v79, v79, v179
	v_exp_f32_e32 v77, v77
	v_add_f32_e32 v235, v235, v74
	v_exp_f32_e32 v78, v78
	v_add_f32_e32 v235, v235, v75
	v_exp_f32_e32 v79, v79
	v_add_f32_e32 v235, v235, v76
	v_add_f32_e32 v235, v235, v77
	v_add_f32_e32 v235, v235, v78
	v_add_f32_e32 v235, v235, v79
	v_add_f32_e32 v169, v169, v235
	v_cvt_pk_bf16_f32 v80, v80, v81
	v_cvt_pk_bf16_f32 v81, v82, v83
	v_cvt_pk_bf16_f32 v82, v84, v85
	v_cvt_pk_bf16_f32 v83, v86, v87
	v_cvt_pk_bf16_f32 v84, v88, v89
	v_cvt_pk_bf16_f32 v85, v90, v91
	v_cvt_pk_bf16_f32 v86, v92, v93
	v_cvt_pk_bf16_f32 v87, v94, v95
	v_cvt_pk_bf16_f32 v64, v64, v65
	v_cvt_pk_bf16_f32 v65, v66, v67
	v_cvt_pk_bf16_f32 v66, v68, v69
	v_cvt_pk_bf16_f32 v67, v70, v71
	v_cvt_pk_bf16_f32 v68, v72, v73
	v_cvt_pk_bf16_f32 v69, v74, v75
	v_cvt_pk_bf16_f32 v70, v76, v77
	v_cvt_pk_bf16_f32 v71, v78, v79
	v_sub_f32_e32 v112, v112, v178
	v_sub_f32_e32 v113, v113, v178
	v_sub_f32_e32 v114, v114, v178
	v_exp_f32_e32 v112, v112
	s_waitcnt lgkmcnt(0)
; #define LAS __attribute__((address_space(3)))
; __device__ __forceinline__ unsigned pk2c(float lo, float hi) { f32x2_t v = {lo, hi}; bf16x2_t b = __builtin_convertvector(v, bf16x2_t); return __builtin_bit_cast(unsigned, b); }
; #define MFMA32(a, b, c) __builtin_amdgcn_mfma_f32_32x32x16_bf16((a), (b), (c), 0, 0, 0)
; template <int DQ, bool BIAS, bool TAIL>
; __device__ __forceinline__ void attn_item(const AttnItem& A, LAS unsigned char* lds, int wave_s_) {
;     ...
;                 if (__builtin_amdgcn_ballot_w64(need0 || need1) != 0ull) {
; #pragma unroll
;                     for (int qb = 0; qb < 2; ++qb) {
;                         const float delta = (qb == 0 ? need0 : need1) ? mx[qb] : 0.f, alpha = __builtin_amdgcn_exp2f(-delta);
; #pragma unroll
;                         for (int i = 0; i < 16; ++i) { o[0][qb][i] *= alpha; o[1][qb][i] *= alpha; }
;                         lrun[qb] *= alpha; mref[qb] += delta;
;                     }
;                     first = false;
;                 }
; #pragma unroll
;                 for (int qb = 0; qb < 2; ++qb) { float l4[4] = {0.f, 0.f, 0.f, 0.f};
; #pragma unroll
;                     for (int i = 0; i < 16; ++i) { const float pv = __builtin_amdgcn_exp2f(s[qb][i] - mref[qb]); s[qb][i] = pv; l4[i & 3] += pv; }
;                     lrun[qb] += (l4[0] + l4[1]) + (l4[2] + l4[3]); }
;                 bf16x8 pf[2][2];
; #pragma unroll
;                 for (int st = 0; st < 2; ++st)
; #pragma unroll
;                     for (int qb = 0; qb < 2; ++qb) { u32x4 pw;
; #pragma unroll
;                         for (int j = 0; j < 4; ++j) pw[j] = pk2c(s[qb][8 * st + 2 * j], s[qb][8 * st + 2 * j + 1]);
;                         pf[st][qb] = __builtin_bit_cast(bf16x8, pw); }
;                 if (kbk == 0) {
; #pragma unroll
;                     for (int kk = 0; kk < NKK; ++kk) kf[kk] = *(const LAS bf16x8*)(kb + (32 * KSTR + 16 * kk) * 2);
;                 }
;                 __builtin_amdgcn_sched_barrier(0);
; #pragma unroll
;                 for (int st = 0; st < 2; ++st)
; #pragma unroll
;                     for (int d = 0; d < 2; ++d) {
;                         const bf16x8 vf = __builtin_shufflevector(vlo[st][d], vhi[st][d], 0, 1, 2, 3, 4, 5, 6, 7);
;                         o[d][0] = MFMA32(vf, pf[st][0], o[d][0]);
;                         o[d][1] = MFMA32(vf, pf[st][1], o[d][1]);
;                     }
	v_mfma_f32_32x32x16_bf16 v[16:31], v[206:209], v[80:83], v[16:31]
	v_sub_f32_e32 v115, v115, v178
	v_exp_f32_e32 v113, v113
	v_sub_f32_e32 v116, v116, v178
	v_exp_f32_e32 v114, v114
	v_sub_f32_e32 v117, v117, v178
	v_exp_f32_e32 v115, v115
	v_sub_f32_e32 v118, v118, v178
	v_exp_f32_e32 v116, v116
	v_add_f32_e32 v196, v112, v113
	v_sub_f32_e32 v119, v119, v178
	v_exp_f32_e32 v117, v117
	v_mfma_f32_32x32x16_bf16 v[0:15], v[210:213], v[80:83], v[0:15]
	v_add_f32_e32 v196, v196, v114
	v_sub_f32_e32 v120, v120, v178
	v_exp_f32_e32 v118, v118
	v_add_f32_e32 v196, v196, v115
	v_sub_f32_e32 v121, v121, v178
	v_exp_f32_e32 v119, v119
	v_add_f32_e32 v196, v196, v116
	v_sub_f32_e32 v122, v122, v178
	v_exp_f32_e32 v120, v120
	v_add_f32_e32 v196, v196, v117
	v_sub_f32_e32 v123, v123, v178
	v_mfma_f32_32x32x16_bf16 v[16:31], v[214:217], v[84:87], v[16:31]
	v_exp_f32_e32 v121, v121
	v_add_f32_e32 v196, v196, v118
	v_sub_f32_e32 v124, v124, v178
	v_exp_f32_e32 v122, v122
	v_add_f32_e32 v196, v196, v119
	v_sub_f32_e32 v125, v125, v178
	v_exp_f32_e32 v123, v123
	v_add_f32_e32 v196, v196, v120
	v_sub_f32_e32 v126, v126, v178
	v_exp_f32_e32 v124, v124
	v_add_f32_e32 v196, v196, v121
	v_mfma_f32_32x32x16_bf16 v[0:15], v[218:221], v[84:87], v[0:15]
	v_sub_f32_e32 v127, v127, v178
	v_exp_f32_e32 v125, v125
	v_add_f32_e32 v196, v196, v122
	v_sub_f32_e32 v96, v96, v178
	v_exp_f32_e32 v126, v126
	v_add_f32_e32 v196, v196, v123
	v_sub_f32_e32 v97, v97, v178
	v_exp_f32_e32 v127, v127
	v_add_f32_e32 v196, v196, v124
	v_sub_f32_e32 v98, v98, v178
	v_exp_f32_e32 v96, v96
	v_mfma_f32_32x32x16_bf16 v[16:31], v[222:225], v[64:67], v[16:31]
	v_add_f32_e32 v196, v196, v125
	v_sub_f32_e32 v99, v99, v178
	v_exp_f32_e32 v97, v97
	v_add_f32_e32 v196, v196, v126
	v_sub_f32_e32 v100, v100, v178
	v_exp_f32_e32 v98, v98
	v_add_f32_e32 v196, v196, v127
	v_sub_f32_e32 v101, v101, v178
	v_exp_f32_e32 v99, v99
	v_add_f32_e32 v196, v196, v96
	v_sub_f32_e32 v102, v102, v178
	v_mfma_f32_32x32x16_bf16 v[0:15], v[226:229], v[64:67], v[0:15]
	v_exp_f32_e32 v100, v100
	v_add_f32_e32 v196, v196, v97
	v_sub_f32_e32 v103, v103, v178
	v_exp_f32_e32 v101, v101
	v_add_f32_e32 v196, v196, v98
	v_sub_f32_e32 v104, v104, v178
	v_exp_f32_e32 v102, v102
	v_add_f32_e32 v196, v196, v99
	v_sub_f32_e32 v105, v105, v178
	v_exp_f32_e32 v103, v103
	v_add_f32_e32 v196, v196, v100
	v_mfma_f32_32x32x16_bf16 v[16:31], v[230:233], v[68:71], v[16:31]
	v_sub_f32_e32 v106, v106, v178
	v_exp_f32_e32 v104, v104
	v_add_f32_e32 v196, v196, v101
	v_sub_f32_e32 v107, v107, v178
	v_exp_f32_e32 v105, v105
	v_add_f32_e32 v196, v196, v102
	v_sub_f32_e32 v108, v108, v178
	v_exp_f32_e32 v106, v106
	v_add_f32_e32 v196, v196, v103
	v_sub_f32_e32 v109, v109, v178
	v_exp_f32_e32 v107, v107
	v_mfma_f32_32x32x16_bf16 v[0:15], v[180:183], v[68:71], v[0:15]
	v_add_f32_e32 v196, v196, v104
	v_sub_f32_e32 v110, v110, v178
	v_exp_f32_e32 v108, v108
	v_add_f32_e32 v196, v196, v105
	v_sub_f32_e32 v111, v111, v178
	v_exp_f32_e32 v109, v109
	v_add_f32_e32 v196, v196, v106
	v_exp_f32_e32 v110, v110
	v_add_f32_e32 v196, v196, v107
	v_exp_f32_e32 v111, v111
	v_add_f32_e32 v196, v196, v108
	v_add_f32_e32 v196, v196, v109
	v_add_f32_e32 v196, v196, v110
	v_add_f32_e32 v196, v196, v111
	v_add_f32_e32 v168, v168, v196
	v_cvt_pk_bf16_f32 v112, v112, v113
	v_cvt_pk_bf16_f32 v113, v114, v115
	v_cvt_pk_bf16_f32 v114, v116, v117
	v_cvt_pk_bf16_f32 v115, v118, v119
	v_cvt_pk_bf16_f32 v116, v120, v121
	v_cvt_pk_bf16_f32 v117, v122, v123
	v_cvt_pk_bf16_f32 v118, v124, v125
	v_cvt_pk_bf16_f32 v119, v126, v127
	v_cvt_pk_bf16_f32 v96, v96, v97
	v_cvt_pk_bf16_f32 v97, v98, v99
	v_cvt_pk_bf16_f32 v98, v100, v101
	v_cvt_pk_bf16_f32 v99, v102, v103
	v_cvt_pk_bf16_f32 v100, v104, v105
	v_cvt_pk_bf16_f32 v101, v106, v107
	v_cvt_pk_bf16_f32 v102, v108, v109
	v_cvt_pk_bf16_f32 v103, v110, v111
	s_nop 1
	v_mfma_f32_32x32x16_bf16 v[32:47], v[206:209], v[112:115], v[32:47]
	v_mfma_f32_32x32x16_bf16 v[48:63], v[210:213], v[112:115], v[48:63]
	v_mfma_f32_32x32x16_bf16 v[32:47], v[214:217], v[116:119], v[32:47]
	v_mfma_f32_32x32x16_bf16 v[48:63], v[218:221], v[116:119], v[48:63]
	v_mfma_f32_32x32x16_bf16 v[32:47], v[222:225], v[96:99], v[32:47]
	v_mfma_f32_32x32x16_bf16 v[48:63], v[226:229], v[96:99], v[48:63]
	v_mfma_f32_32x32x16_bf16 v[32:47], v[230:233], v[100:103], v[32:47]
	v_mfma_f32_32x32x16_bf16 v[48:63], v[180:183], v[100:103], v[48:63]
	s_branch .LBB0_1040
.La0_rare:
	s_nop 15
	v_mov_b32_e32 v241, v235
	s_nop 1
	v_permlane32_swap_b32_e32 v241, v235
	v_max_f32_e32 v239, v241, v235
	v_cndmask_b32_e64 v239, v179, v239, s[10:11]
	v_sub_f32_e32 v177, v179, v239
	v_exp_f32_e32 v177, v177
	v_mov_b32_e32 v179, v239
	v_mul_f32_e32 v16, v16, v177
	v_mul_f32_e32 v17, v17, v177
	v_mul_f32_e32 v18, v18, v177
	v_mul_f32_e32 v19, v19, v177
	v_mul_f32_e32 v20, v20, v177
	v_mul_f32_e32 v21, v21, v177
	v_mul_f32_e32 v22, v22, v177
	v_mul_f32_e32 v23, v23, v177
	v_mul_f32_e32 v24, v24, v177
	v_mul_f32_e32 v25, v25, v177
	v_mul_f32_e32 v26, v26, v177
	v_mul_f32_e32 v27, v27, v177
	v_mul_f32_e32 v28, v28, v177
	v_mul_f32_e32 v29, v29, v177
	v_mul_f32_e32 v30, v30, v177
	v_mul_f32_e32 v31, v31, v177
	v_mul_f32_e32 v0, v0, v177
	v_mul_f32_e32 v1, v1, v177
	v_mul_f32_e32 v2, v2, v177
	v_mul_f32_e32 v3, v3, v177
	v_mul_f32_e32 v4, v4, v177
	v_mul_f32_e32 v5, v5, v177
	v_mul_f32_e32 v6, v6, v177
	v_mul_f32_e32 v7, v7, v177
	v_mul_f32_e32 v8, v8, v177
	v_mul_f32_e32 v9, v9, v177
	v_mul_f32_e32 v10, v10, v177
	v_mul_f32_e32 v11, v11, v177
	v_mul_f32_e32 v12, v12, v177
	v_mul_f32_e32 v13, v13, v177
	v_mul_f32_e32 v14, v14, v177
	v_mul_f32_e32 v15, v15, v177
	v_mul_f32_e32 v169, v169, v177
	v_mov_b32_e32 v240, v234
	s_nop 1
	v_permlane32_swap_b32_e32 v240, v234
	v_max_f32_e32 v238, v240, v234
	v_cndmask_b32_e64 v238, v178, v238, s[8:9]
	v_sub_f32_e32 v176, v178, v238
	v_exp_f32_e32 v176, v176
	v_mov_b32_e32 v178, v238
	v_mul_f32_e32 v32, v32, v176
	v_mul_f32_e32 v33, v33, v176
	v_mul_f32_e32 v34, v34, v176
	v_mul_f32_e32 v35, v35, v176
	v_mul_f32_e32 v36, v36, v176
	v_mul_f32_e32 v37, v37, v176
	v_mul_f32_e32 v38, v38, v176
	v_mul_f32_e32 v39, v39, v176
	v_mul_f32_e32 v40, v40, v176
	v_mul_f32_e32 v41, v41, v176
	v_mul_f32_e32 v42, v42, v176
	v_mul_f32_e32 v43, v43, v176
	v_mul_f32_e32 v44, v44, v176
	v_mul_f32_e32 v45, v45, v176
	v_mul_f32_e32 v46, v46, v176
	v_mul_f32_e32 v47, v47, v176
	v_mul_f32_e32 v48, v48, v176
	v_mul_f32_e32 v49, v49, v176
	v_mul_f32_e32 v50, v50, v176
	v_mul_f32_e32 v51, v51, v176
	v_mul_f32_e32 v52, v52, v176
	v_mul_f32_e32 v53, v53, v176
	v_mul_f32_e32 v54, v54, v176
	v_mul_f32_e32 v55, v55, v176
	v_mul_f32_e32 v56, v56, v176
	v_mul_f32_e32 v57, v57, v176
	v_mul_f32_e32 v58, v58, v176
	v_mul_f32_e32 v59, v59, v176
	v_mul_f32_e32 v60, v60, v176
	v_mul_f32_e32 v61, v61, v176
	v_mul_f32_e32 v62, v62, v176
	v_mul_f32_e32 v63, v63, v176
	v_mul_f32_e32 v168, v168, v176
	s_branch .La0_back
